# final-norm epilogue: residual loads issued two row groups ahead (8 loads in flight instead of 2), on top of v22
# speedup vs baseline: 1.0071x; 1.0071x over previous
.LBB0_991:
	s_mov_b32 s34, s77
	s_lshl_b32 s56, s59, 2
	v_lshl_add_u32 v154, s58, 8, v184
	v_ashrrev_i32_e32 v155, 31, v154
	v_lshl_or_b32 v146, s59, 8, v186
	v_lshlrev_b64 v[142:143], 12, v[154:155]
	v_ashrrev_i32_e32 v147, 31, v146
	v_lshl_add_u64 v[142:143], s[12:13], 0, v[142:143]
	v_lshl_add_u64 v[142:143], v[146:147], 2, v[142:143]
	v_lshlrev_b32_e32 v193, 12, v154
	v_lshl_add_u32 v193, v146, 2, v193
	s_mov_b64 s[100:101], s[12:13]
	global_load_dwordx4 v[194:197], v193, s[100:101] offset:16
	global_load_dwordx4 v[198:201], v193, s[100:101]
	global_load_dwordx4 v[202:205], v193, s[100:101] offset:528
	global_load_dwordx4 v[206:209], v193, s[100:101] offset:512
	s_add_u32 s100, s12, 0x10000
	s_addc_u32 s101, s13, 0
	global_load_dwordx4 v[214:217], v193, s[100:101] offset:16
	global_load_dwordx4 v[218:221], v193, s[100:101]
	global_load_dwordx4 v[222:225], v193, s[100:101] offset:528
	global_load_dwordx4 v[230:233], v193, s[100:101] offset:512
	s_ashr_i32 s57, s56, 31
	s_waitcnt vmcnt(6)
	v_pk_add_f32 v[124:125], v[124:125], v[196:197]
	v_pk_add_f32 v[128:129], v[128:129], v[200:201]
	v_pk_add_f32 v[126:127], v[126:127], v[198:199]
	v_pk_add_f32 v[122:123], v[122:123], v[194:195]
	v_mul_f32_e32 v144, v127, v127
	v_mul_f32_e32 v145, v129, v129
	v_fmac_f32_e32 v144, v126, v126
	v_fmac_f32_e32 v145, v128, v128
	v_add_f32_e32 v144, v144, v145
	v_mul_f32_e32 v145, v123, v123
	v_fmac_f32_e32 v145, v122, v122
	v_add_f32_e32 v144, v144, v145
	v_mul_f32_e32 v145, v125, v125
	v_fmac_f32_e32 v145, v124, v124
	v_add_f32_e32 v144, v145, v144
	s_waitcnt vmcnt(4)
	v_pk_add_f32 v[114:115], v[114:115], v[202:203]
	v_pk_add_f32 v[120:121], v[120:121], v[208:209]
	v_pk_add_f32 v[118:119], v[118:119], v[206:207]
	v_mul_f32_e32 v148, v121, v121
	v_mul_f32_e32 v145, v119, v119
	v_fmac_f32_e32 v145, v118, v118
	v_fmac_f32_e32 v148, v120, v120
	v_add_f32_e32 v145, v145, v148
	v_mul_f32_e32 v148, v115, v115
	v_pk_add_f32 v[116:117], v[116:117], v[204:205]
	v_fmac_f32_e32 v148, v114, v114
	v_add_f32_e32 v145, v145, v148
	v_mul_f32_e32 v148, v117, v117
	v_fmac_f32_e32 v148, v116, v116
	v_add_f32_e32 v145, v148, v145
	v_add_f32_e32 v144, v144, v145
	ds_swizzle_b32 v145, v144 offset:swizzle(SWAP,16)
	v_lshlrev_b64 v[150:151], 6, v[154:155]
	s_waitcnt lgkmcnt(0)
	v_add_f32_e32 v144, v144, v145
	v_mov_b32_e32 v145, v144
	s_nop 1
	v_permlane32_swap_b32_e32 v144, v145
	s_and_saveexec_b64 s[34:35], s[8:9]
	s_cbranch_execz .LBB0_993
	v_add_f32_e32 v148, v144, v145
	v_lshl_add_u64 v[144:145], s[18:19], 0, v[150:151]
	v_lshl_add_u64 v[144:145], s[56:57], 2, v[144:145]
	s_lshl_b32 s76, s45, 2
	v_lshl_add_u64 v[144:145], v[144:145], 0, s[76:77]
	global_store_dword v[144:145], v148, off sc1
.LBB0_993:
	s_or_b64 exec, exec, s[34:35]
	v_or_b32_e32 v148, 16, v154
	v_ashrrev_i32_e32 v149, 31, v148
	v_lshlrev_b64 v[144:145], 12, v[148:149]
	v_lshl_add_u64 v[144:145], s[12:13], 0, v[144:145]
	v_lshl_add_u64 v[144:145], v[146:147], 2, v[144:145]
	s_add_u32 s100, s12, 0x20000
	s_addc_u32 s101, s13, 0
	global_load_dwordx4 v[194:197], v193, s[100:101] offset:16
	global_load_dwordx4 v[198:201], v193, s[100:101]
	global_load_dwordx4 v[202:205], v193, s[100:101] offset:528
	global_load_dwordx4 v[206:209], v193, s[100:101] offset:512
	s_waitcnt vmcnt(6)
	v_pk_add_f32 v[108:109], v[108:109], v[216:217]
	s_waitcnt vmcnt(6)
	v_pk_add_f32 v[112:113], v[112:113], v[220:221]
	v_pk_add_f32 v[110:111], v[110:111], v[218:219]
	v_pk_add_f32 v[106:107], v[106:107], v[214:215]
	v_mul_f32_e32 v152, v111, v111
	v_mul_f32_e32 v153, v113, v113
	v_fmac_f32_e32 v152, v110, v110
	v_fmac_f32_e32 v153, v112, v112
	v_add_f32_e32 v152, v152, v153
	v_mul_f32_e32 v153, v107, v107
	v_fmac_f32_e32 v153, v106, v106
	v_add_f32_e32 v152, v152, v153
	v_mul_f32_e32 v153, v109, v109
	v_fmac_f32_e32 v153, v108, v108
	v_add_f32_e32 v152, v153, v152
	s_waitcnt vmcnt(4)
	v_pk_add_f32 v[98:99], v[98:99], v[222:223]
	s_waitcnt vmcnt(4)
	v_pk_add_f32 v[104:105], v[104:105], v[232:233]
	v_pk_add_f32 v[102:103], v[102:103], v[230:231]
	v_mul_f32_e32 v155, v105, v105
	v_mul_f32_e32 v153, v103, v103
	v_fmac_f32_e32 v153, v102, v102
	v_fmac_f32_e32 v155, v104, v104
	v_add_f32_e32 v153, v153, v155
	v_mul_f32_e32 v155, v99, v99
	v_pk_add_f32 v[100:101], v[100:101], v[224:225]
	v_fmac_f32_e32 v155, v98, v98
	v_add_f32_e32 v153, v153, v155
	v_mul_f32_e32 v155, v101, v101
	v_fmac_f32_e32 v155, v100, v100
	v_add_f32_e32 v153, v155, v153
	v_add_f32_e32 v152, v152, v153
	ds_swizzle_b32 v153, v152 offset:swizzle(SWAP,16)
	v_lshlrev_b64 v[156:157], 6, v[148:149]
	s_waitcnt lgkmcnt(0)
	v_add_f32_e32 v152, v152, v153
	v_mov_b32_e32 v153, v152
	s_nop 1
	v_permlane32_swap_b32_e32 v152, v153
	s_and_saveexec_b64 s[34:35], s[8:9]
	s_cbranch_execz .LBB0_995
	v_lshl_add_u64 v[148:149], s[18:19], 0, v[156:157]
	v_lshl_add_u64 v[148:149], s[56:57], 2, v[148:149]
	s_lshl_b32 s76, s45, 2
	v_add_f32_e32 v152, v152, v153
	v_lshl_add_u64 v[148:149], v[148:149], 0, s[76:77]
	global_store_dword v[148:149], v152, off sc1
.LBB0_995:
	s_or_b64 exec, exec, s[34:35]
	v_or_b32_e32 v152, 32, v154
	v_ashrrev_i32_e32 v153, 31, v152
	v_lshlrev_b64 v[148:149], 12, v[152:153]
	v_lshl_add_u64 v[148:149], s[12:13], 0, v[148:149]
	v_lshl_add_u64 v[148:149], v[146:147], 2, v[148:149]
	s_add_u32 s100, s12, 0x30000
	s_addc_u32 s101, s13, 0
	global_load_dwordx4 v[214:217], v193, s[100:101] offset:16
	global_load_dwordx4 v[218:221], v193, s[100:101]
	global_load_dwordx4 v[222:225], v193, s[100:101] offset:528
	global_load_dwordx4 v[230:233], v193, s[100:101] offset:512
	s_waitcnt vmcnt(6)
	v_pk_add_f32 v[90:91], v[90:91], v[194:195]
	s_waitcnt vmcnt(6)
	v_pk_add_f32 v[96:97], v[96:97], v[200:201]
	v_pk_add_f32 v[94:95], v[94:95], v[198:199]
	v_mul_f32_e32 v158, v97, v97
	v_mul_f32_e32 v155, v95, v95
	v_fmac_f32_e32 v155, v94, v94
	v_fmac_f32_e32 v158, v96, v96
	v_add_f32_e32 v155, v155, v158
	v_mul_f32_e32 v158, v91, v91
	v_pk_add_f32 v[92:93], v[92:93], v[196:197]
	v_fmac_f32_e32 v158, v90, v90
	v_add_f32_e32 v155, v155, v158
	v_mul_f32_e32 v158, v93, v93
	v_fmac_f32_e32 v158, v92, v92
	v_add_f32_e32 v155, v158, v155
	s_waitcnt vmcnt(4)
	v_pk_add_f32 v[82:83], v[82:83], v[202:203]
	s_waitcnt vmcnt(4)
	v_pk_add_f32 v[88:89], v[88:89], v[208:209]
	v_pk_add_f32 v[86:87], v[86:87], v[206:207]
	v_mul_f32_e32 v159, v89, v89
	v_mul_f32_e32 v158, v87, v87
	v_fmac_f32_e32 v158, v86, v86
	v_fmac_f32_e32 v159, v88, v88
	v_add_f32_e32 v158, v158, v159
	v_mul_f32_e32 v159, v83, v83
	v_pk_add_f32 v[84:85], v[84:85], v[204:205]
	v_fmac_f32_e32 v159, v82, v82
	v_add_f32_e32 v158, v158, v159
	v_mul_f32_e32 v159, v85, v85
	v_fmac_f32_e32 v159, v84, v84
	v_add_f32_e32 v158, v159, v158
	v_add_f32_e32 v155, v155, v158
	ds_swizzle_b32 v158, v155 offset:swizzle(SWAP,16)
	v_lshlrev_b64 v[160:161], 6, v[152:153]
	s_waitcnt lgkmcnt(0)
	v_add_f32_e32 v155, v155, v158
	v_mov_b32_e32 v158, v155
	s_nop 1
	v_permlane32_swap_b32_e32 v155, v158
	s_and_saveexec_b64 s[34:35], s[8:9]
	s_cbranch_execz .LBB0_997
	v_lshl_add_u64 v[152:153], s[18:19], 0, v[160:161]
	v_lshl_add_u64 v[152:153], s[56:57], 2, v[152:153]
	s_lshl_b32 s76, s45, 2
	v_add_f32_e32 v155, v155, v158
	v_lshl_add_u64 v[152:153], v[152:153], 0, s[76:77]
	global_store_dword v[152:153], v155, off sc1
.LBB0_997:
	s_or_b64 exec, exec, s[34:35]
	v_or_b32_e32 v158, 48, v154
	v_ashrrev_i32_e32 v159, 31, v158
	v_lshlrev_b64 v[152:153], 12, v[158:159]
	v_lshl_add_u64 v[152:153], s[12:13], 0, v[152:153]
	v_lshl_add_u64 v[152:153], v[146:147], 2, v[152:153]
	s_add_u32 s100, s12, 0x80000
	s_addc_u32 s101, s13, 0
	global_load_dwordx4 v[194:197], v193, s[100:101] offset:16
	global_load_dwordx4 v[198:201], v193, s[100:101]
	global_load_dwordx4 v[202:205], v193, s[100:101] offset:528
	global_load_dwordx4 v[206:209], v193, s[100:101] offset:512
	s_waitcnt vmcnt(6)
	v_pk_add_f32 v[74:75], v[74:75], v[214:215]
	s_waitcnt vmcnt(6)
	v_pk_add_f32 v[80:81], v[80:81], v[220:221]
	v_pk_add_f32 v[78:79], v[78:79], v[218:219]
	v_mul_f32_e32 v162, v81, v81
	v_mul_f32_e32 v155, v79, v79
	v_fmac_f32_e32 v155, v78, v78
	v_fmac_f32_e32 v162, v80, v80
	v_add_f32_e32 v155, v155, v162
	v_mul_f32_e32 v162, v75, v75
	v_pk_add_f32 v[76:77], v[76:77], v[216:217]
	v_fmac_f32_e32 v162, v74, v74
	v_add_f32_e32 v155, v155, v162
	v_mul_f32_e32 v162, v77, v77
	v_fmac_f32_e32 v162, v76, v76
	v_add_f32_e32 v155, v162, v155
	s_waitcnt vmcnt(4)
	v_pk_add_f32 v[66:67], v[66:67], v[222:223]
	s_waitcnt vmcnt(4)
	v_pk_add_f32 v[72:73], v[72:73], v[232:233]
	v_pk_add_f32 v[70:71], v[70:71], v[230:231]
	v_mul_f32_e32 v163, v73, v73
	v_mul_f32_e32 v162, v71, v71
	v_fmac_f32_e32 v162, v70, v70
	v_fmac_f32_e32 v163, v72, v72
	v_add_f32_e32 v162, v162, v163
	v_mul_f32_e32 v163, v67, v67
	v_pk_add_f32 v[68:69], v[68:69], v[224:225]
	v_fmac_f32_e32 v163, v66, v66
	v_add_f32_e32 v162, v162, v163
	v_mul_f32_e32 v163, v69, v69
	v_fmac_f32_e32 v163, v68, v68
	v_add_f32_e32 v162, v163, v162
	v_add_f32_e32 v155, v155, v162
	ds_swizzle_b32 v162, v155 offset:swizzle(SWAP,16)
	v_lshlrev_b64 v[164:165], 6, v[158:159]
	s_waitcnt lgkmcnt(0)
	v_add_f32_e32 v155, v155, v162
	v_mov_b32_e32 v162, v155
	s_nop 1
	v_permlane32_swap_b32_e32 v155, v162
	s_and_saveexec_b64 s[34:35], s[8:9]
	s_cbranch_execz .LBB0_999
	v_lshl_add_u64 v[158:159], s[18:19], 0, v[164:165]
	v_lshl_add_u64 v[158:159], s[56:57], 2, v[158:159]
	s_lshl_b32 s76, s45, 2
	v_add_f32_e32 v155, v155, v162
	v_lshl_add_u64 v[158:159], v[158:159], 0, s[76:77]
	global_store_dword v[158:159], v155, off sc1
.LBB0_999:
	s_or_b64 exec, exec, s[34:35]
	v_add_u32_e32 v162, 0x80, v154
	v_ashrrev_i32_e32 v163, 31, v162
	v_lshlrev_b64 v[158:159], 12, v[162:163]
	v_lshl_add_u64 v[158:159], s[12:13], 0, v[158:159]
	v_lshl_add_u64 v[158:159], v[146:147], 2, v[158:159]
	s_add_u32 s100, s12, 0x90000
	s_addc_u32 s101, s13, 0
	global_load_dwordx4 v[214:217], v193, s[100:101] offset:16
	global_load_dwordx4 v[218:221], v193, s[100:101]
	global_load_dwordx4 v[222:225], v193, s[100:101] offset:528
	global_load_dwordx4 v[230:233], v193, s[100:101] offset:512
	s_waitcnt vmcnt(6)
	v_pk_add_f32 v[58:59], v[58:59], v[194:195]
	s_waitcnt vmcnt(6)
	v_pk_add_f32 v[64:65], v[64:65], v[200:201]
	v_pk_add_f32 v[62:63], v[62:63], v[198:199]
	v_mul_f32_e32 v166, v65, v65
	v_mul_f32_e32 v155, v63, v63
	v_fmac_f32_e32 v155, v62, v62
	v_fmac_f32_e32 v166, v64, v64
	v_add_f32_e32 v155, v155, v166
	v_mul_f32_e32 v166, v59, v59
	v_pk_add_f32 v[60:61], v[60:61], v[196:197]
	v_fmac_f32_e32 v166, v58, v58
	v_add_f32_e32 v155, v155, v166
	v_mul_f32_e32 v166, v61, v61
	v_fmac_f32_e32 v166, v60, v60
	v_add_f32_e32 v155, v166, v155
	s_waitcnt vmcnt(4)
	v_pk_add_f32 v[50:51], v[50:51], v[202:203]
	s_waitcnt vmcnt(4)
	v_pk_add_f32 v[56:57], v[56:57], v[208:209]
	v_pk_add_f32 v[54:55], v[54:55], v[206:207]
	v_mul_f32_e32 v167, v57, v57
	v_mul_f32_e32 v166, v55, v55
	v_fmac_f32_e32 v166, v54, v54
	v_fmac_f32_e32 v167, v56, v56
	v_add_f32_e32 v166, v166, v167
	v_mul_f32_e32 v167, v51, v51
	v_pk_add_f32 v[52:53], v[52:53], v[204:205]
	v_fmac_f32_e32 v167, v50, v50
	v_add_f32_e32 v166, v166, v167
	v_mul_f32_e32 v167, v53, v53
	v_fmac_f32_e32 v167, v52, v52
	v_add_f32_e32 v166, v167, v166
	v_add_f32_e32 v155, v155, v166
	ds_swizzle_b32 v166, v155 offset:swizzle(SWAP,16)
	v_lshlrev_b64 v[168:169], 6, v[162:163]
	s_waitcnt lgkmcnt(0)
	v_add_f32_e32 v155, v155, v166
	v_mov_b32_e32 v166, v155
	s_nop 1
	v_permlane32_swap_b32_e32 v155, v166
	s_and_saveexec_b64 s[34:35], s[8:9]
	s_cbranch_execz .LBB0_1001
	v_lshl_add_u64 v[162:163], s[18:19], 0, v[168:169]
	v_lshl_add_u64 v[162:163], s[56:57], 2, v[162:163]
	s_lshl_b32 s76, s45, 2
	v_add_f32_e32 v155, v155, v166
	v_lshl_add_u64 v[162:163], v[162:163], 0, s[76:77]
	global_store_dword v[162:163], v155, off sc1
.LBB0_1001:
	s_or_b64 exec, exec, s[34:35]
	v_add_u32_e32 v166, 0x90, v154
	v_ashrrev_i32_e32 v167, 31, v166
	v_lshlrev_b64 v[162:163], 12, v[166:167]
	v_lshl_add_u64 v[162:163], s[12:13], 0, v[162:163]
	v_lshl_add_u64 v[162:163], v[146:147], 2, v[162:163]
	s_add_u32 s100, s12, 0xa0000
	s_addc_u32 s101, s13, 0
	global_load_dwordx4 v[194:197], v193, s[100:101] offset:16
	global_load_dwordx4 v[198:201], v193, s[100:101]
	global_load_dwordx4 v[202:205], v193, s[100:101] offset:528
	global_load_dwordx4 v[206:209], v193, s[100:101] offset:512
	v_lshlrev_b64 v[178:179], 6, v[166:167]
	s_waitcnt vmcnt(6)
	v_pk_add_f32 v[42:43], v[42:43], v[214:215]
	s_waitcnt vmcnt(6)
	v_pk_add_f32 v[48:49], v[48:49], v[220:221]
	v_pk_add_f32 v[46:47], v[46:47], v[218:219]
	v_mul_f32_e32 v170, v49, v49
	v_mul_f32_e32 v155, v47, v47
	v_fmac_f32_e32 v155, v46, v46
	v_fmac_f32_e32 v170, v48, v48
	v_add_f32_e32 v155, v155, v170
	v_mul_f32_e32 v170, v43, v43
	v_pk_add_f32 v[44:45], v[44:45], v[216:217]
	v_fmac_f32_e32 v170, v42, v42
	v_add_f32_e32 v155, v155, v170
	v_mul_f32_e32 v170, v45, v45
	v_fmac_f32_e32 v170, v44, v44
	v_add_f32_e32 v155, v170, v155
	s_waitcnt vmcnt(4)
	v_pk_add_f32 v[34:35], v[34:35], v[222:223]
	s_waitcnt vmcnt(4)
	v_pk_add_f32 v[40:41], v[40:41], v[232:233]
	v_pk_add_f32 v[38:39], v[38:39], v[230:231]
	v_mul_f32_e32 v171, v41, v41
	v_mul_f32_e32 v170, v39, v39
	v_fmac_f32_e32 v170, v38, v38
	v_fmac_f32_e32 v171, v40, v40
	v_add_f32_e32 v170, v170, v171
	v_mul_f32_e32 v171, v35, v35
	v_pk_add_f32 v[36:37], v[36:37], v[224:225]
	v_fmac_f32_e32 v171, v34, v34
	v_add_f32_e32 v170, v170, v171
	v_mul_f32_e32 v171, v37, v37
	v_fmac_f32_e32 v171, v36, v36
	v_add_f32_e32 v170, v171, v170
	v_add_f32_e32 v155, v155, v170
	ds_swizzle_b32 v170, v155 offset:swizzle(SWAP,16)
	s_waitcnt lgkmcnt(0)
	v_add_f32_e32 v155, v155, v170
	v_mov_b32_e32 v170, v155
	s_nop 1
	v_permlane32_swap_b32_e32 v155, v170
	s_and_saveexec_b64 s[34:35], s[8:9]
	s_cbranch_execz .LBB0_1003
	v_lshl_add_u64 v[166:167], s[18:19], 0, v[178:179]
	v_lshl_add_u64 v[166:167], s[56:57], 2, v[166:167]
	s_lshl_b32 s76, s45, 2
	v_add_f32_e32 v155, v155, v170
	v_lshl_add_u64 v[166:167], v[166:167], 0, s[76:77]
	global_store_dword v[166:167], v155, off sc1
.LBB0_1003:
	s_or_b64 exec, exec, s[34:35]
	v_add_u32_e32 v170, 0xa0, v154
	v_ashrrev_i32_e32 v171, 31, v170
	v_lshlrev_b64 v[166:167], 12, v[170:171]
	v_lshl_add_u64 v[166:167], s[12:13], 0, v[166:167]
	v_lshl_add_u64 v[166:167], v[146:147], 2, v[166:167]
	s_add_u32 s100, s12, 0xb0000
	s_addc_u32 s101, s13, 0
	global_load_dwordx4 v[214:217], v193, s[100:101] offset:16
	global_load_dwordx4 v[218:221], v193, s[100:101]
	global_load_dwordx4 v[222:225], v193, s[100:101] offset:528
	global_load_dwordx4 v[230:233], v193, s[100:101] offset:512
	s_waitcnt vmcnt(6)
	v_pk_add_f32 v[26:27], v[26:27], v[194:195]
	s_waitcnt vmcnt(6)
	v_pk_add_f32 v[32:33], v[32:33], v[200:201]
	v_pk_add_f32 v[30:31], v[30:31], v[198:199]
	v_mul_f32_e32 v172, v33, v33
	v_mul_f32_e32 v155, v31, v31
	v_fmac_f32_e32 v155, v30, v30
	v_fmac_f32_e32 v172, v32, v32
	v_add_f32_e32 v155, v155, v172
	v_mul_f32_e32 v172, v27, v27
	v_pk_add_f32 v[28:29], v[28:29], v[196:197]
	v_fmac_f32_e32 v172, v26, v26
	v_add_f32_e32 v155, v155, v172
	v_mul_f32_e32 v172, v29, v29
	v_fmac_f32_e32 v172, v28, v28
	v_add_f32_e32 v155, v172, v155
	s_waitcnt vmcnt(4)
	v_pk_add_f32 v[18:19], v[18:19], v[202:203]
	s_waitcnt vmcnt(4)
	v_pk_add_f32 v[24:25], v[24:25], v[208:209]
	v_pk_add_f32 v[22:23], v[22:23], v[206:207]
	v_mul_f32_e32 v173, v25, v25
	v_mul_f32_e32 v172, v23, v23
	v_fmac_f32_e32 v172, v22, v22
	v_fmac_f32_e32 v173, v24, v24
	v_add_f32_e32 v172, v172, v173
	v_mul_f32_e32 v173, v19, v19
	v_pk_add_f32 v[20:21], v[20:21], v[204:205]
	v_fmac_f32_e32 v173, v18, v18
	v_add_f32_e32 v172, v172, v173
	v_mul_f32_e32 v173, v21, v21
	v_fmac_f32_e32 v173, v20, v20
	v_add_f32_e32 v172, v173, v172
	v_add_f32_e32 v155, v155, v172
	ds_swizzle_b32 v172, v155 offset:swizzle(SWAP,16)
	v_lshlrev_b64 v[180:181], 6, v[170:171]
	s_waitcnt lgkmcnt(0)
	v_add_f32_e32 v155, v155, v172
	v_mov_b32_e32 v172, v155
	s_nop 1
	v_permlane32_swap_b32_e32 v155, v172
	s_and_saveexec_b64 s[34:35], s[8:9]
	s_cbranch_execz .LBB0_1005
	v_lshl_add_u64 v[170:171], s[18:19], 0, v[180:181]
	v_lshl_add_u64 v[170:171], s[56:57], 2, v[170:171]
	s_lshl_b32 s76, s45, 2
	v_add_f32_e32 v155, v155, v172
	v_lshl_add_u64 v[170:171], v[170:171], 0, s[76:77]
	global_store_dword v[170:171], v155, off sc1
.LBB0_1005:
	s_or_b64 exec, exec, s[34:35]
	v_add_u32_e32 v182, 0xb0, v154
	v_ashrrev_i32_e32 v183, 31, v182
	v_lshlrev_b64 v[154:155], 12, v[182:183]
	v_lshl_add_u64 v[154:155], s[12:13], 0, v[154:155]
	v_lshl_add_u64 v[154:155], v[146:147], 2, v[154:155]
	s_waitcnt vmcnt(2)
	v_pk_add_f32 v[174:175], v[16:17], v[220:221]
	v_pk_add_f32 v[176:177], v[14:15], v[218:219]
	v_pk_add_f32 v[172:173], v[10:11], v[214:215]
	v_mul_f32_e32 v10, v177, v177
	v_mul_f32_e32 v11, v175, v175
	v_fmac_f32_e32 v10, v176, v176
	v_fmac_f32_e32 v11, v174, v174
	v_add_f32_e32 v10, v10, v11
	v_mul_f32_e32 v11, v173, v173
	v_pk_add_f32 v[170:171], v[12:13], v[216:217]
	v_fmac_f32_e32 v11, v172, v172
	v_add_f32_e32 v10, v10, v11
	v_mul_f32_e32 v11, v171, v171
	v_fmac_f32_e32 v11, v170, v170
	v_add_f32_e32 v192, v11, v10
	s_waitcnt vmcnt(0)
	v_pk_add_f32 v[14:15], v[8:9], v[232:233]
	v_pk_add_f32 v[16:17], v[6:7], v[230:231]
	v_pk_add_f32 v[12:13], v[2:3], v[222:223]
	v_mul_f32_e32 v2, v17, v17
	v_mul_f32_e32 v3, v15, v15
	v_fmac_f32_e32 v2, v16, v16
	v_fmac_f32_e32 v3, v14, v14
	v_add_f32_e32 v2, v2, v3
	v_mul_f32_e32 v3, v13, v13
	v_pk_add_f32 v[10:11], v[4:5], v[224:225]
	v_fmac_f32_e32 v3, v12, v12
	v_add_f32_e32 v2, v2, v3
	v_mul_f32_e32 v3, v11, v11
	v_fmac_f32_e32 v3, v10, v10
	v_add_f32_e32 v2, v3, v2
	v_add_f32_e32 v2, v192, v2
	ds_swizzle_b32 v3, v2 offset:swizzle(SWAP,16)
	s_waitcnt lgkmcnt(0)
	v_add_f32_e32 v4, v2, v3
	v_mov_b32_e32 v5, v4
	s_nop 1
	v_permlane32_swap_b32_e32 v4, v5
	v_lshlrev_b64 v[2:3], 6, v[182:183]
	s_and_saveexec_b64 s[34:35], s[8:9]
	s_cbranch_execz .LBB0_1007
	v_add_f32_e32 v6, v4, v5
	v_lshl_add_u64 v[4:5], s[18:19], 0, v[2:3]
	v_lshl_add_u64 v[4:5], s[56:57], 2, v[4:5]
	s_lshl_b32 s76, s45, 2
	v_lshl_add_u64 v[4:5], v[4:5], 0, s[76:77]
	global_store_dword v[4:5], v6, off sc1
